# heavy diff loop: all LDS-DMA tile staging issued by waves 0-3 (the half that idles at the step barrier), waves 4-7 issue none
# baseline (speedup 1.0000x reference)
.LBB0_301:
	s_add_i32 s81, s70, s74
	s_add_i32 s82, s81, -2
	s_add_i32 s4, s81, -4
	s_cmp_lt_i32 s4, s68
	s_cselect_b32 s4, s4, s82
	s_add_i32 s5, s81, -3
	s_add_i32 s8, s81, -1
	s_cmp_lt_i32 s5, s68
	s_cselect_b32 s80, s5, s8
	s_lshl_b32 s100, s4, 14
	ds_read_b128 v[200:203], v171
	ds_read_b128 v[204:207], v171 offset:4096
	ds_read_b128 v[208:211], v174
	ds_read_b128 v[212:215], v174 offset:4096
	s_lshl_b32 s5, s4, 6
	s_cmp_lt_i32 s4, s68
	v_subrev_u32_e32 v96, s5, v159
	v_sub_u32_e32 v97, 0, v96
	s_cselect_b64 s[4:5], -1, 0
	v_cndmask_b32_e64 v96, v97, v96, s[4:5]
	v_cvt_f32_i32_e32 v96, v96
	v_cndmask_b32_e64 v99, v187, v186, s[4:5]
	v_cndmask_b32_e32 v128, 0, v99, vcc
	v_mul_f32_e64 v97, -v160, v96
	v_cvt_pk_bf16_f32 v97, v97, 0
	v_lshlrev_b32_e32 v97, 16, v97
	v_fma_f32 v96, -v160, v96, -v97
	v_cvt_pk_bf16_f32 v98, v96, 0
	v_lshlrev_b32_e32 v98, 16, v98
	v_sub_f32_e32 v96, v96, v98
	v_cvt_pk_bf16_f32 v97, v97, v98
	v_cvt_pk_bf16_f32 v96, v96, 0
	v_cndmask_b32_e32 v129, 0, v97, vcc
	v_cndmask_b32_e32 v130, 0, v96, vcc
	v_exp_f32_e32 v80, v80
	v_exp_f32_e32 v81, v81
	v_add_f32_e32 v192, 0, v80
	v_add_f32_e32 v192, v81, v192
	v_mfma_f32_32x32x16_bf16 v[112:127], v[152:155], v[128:131], 0
	s_cmp_lg_u32 s37, 0
	s_cbranch_scc1 .Lhv_skipA1
	v_lshl_add_u32 v240, s80, 13, v185
	s_mov_b32 m0, s76
	v_add_u32_e32 v241, 0x1000, v240
	global_load_lds_dwordx4 v240, s[22:23]
	s_mov_b32 m0, s77
	s_nop 0
	global_load_lds_dwordx4 v240, s[24:25]
	s_add_i32 m0, s76, 0x1000
	s_nop 0
	global_load_lds_dwordx4 v241, s[22:23]
	s_add_i32 m0, s77, 0x1000
	s_nop 0
	global_load_lds_dwordx4 v241, s[24:25]
.Lhv_skipA1:
	v_mfma_f32_32x32x16_bf16 v[96:111], v[148:151], v[128:131], 0
	v_exp_f32_e32 v82, v82
	v_exp_f32_e32 v83, v83
	v_add_f32_e32 v192, v82, v192
	v_add_f32_e32 v192, v83, v192
	s_waitcnt lgkmcnt(3)
	v_mfma_f32_32x32x16_bf16 v[112:127], v[200:203], v[144:147], v[112:127]
	ds_read_b128 v[216:219], v172
	ds_read_b128 v[220:223], v172 offset:4096
	ds_read_b128 v[224:227], v173
	ds_read_b128 v[228:231], v173 offset:4096
	s_cmp_lg_u32 s37, 0
	s_cbranch_scc1 .Lhv_skipA2
	v_add_u32_e32 v240, s100, v170
	s_mov_b32 m0, s71
	v_add_u32_e32 v241, s100, v169
	global_load_lds_dwordx4 v240, s[6:7]
	s_mov_b32 m0, s72
	v_add_u32_e32 v240, 0x1000, v240
	global_load_lds_dwordx4 v241, s[6:7]
	s_add_i32 m0, s71, 0x1000
	v_add_u32_e32 v241, 0x1000, v241
	global_load_lds_dwordx4 v240, s[6:7]
	s_add_i32 m0, s72, 0x1000
	s_nop 0
	global_load_lds_dwordx4 v241, s[6:7]
.Lhv_skipA2:
	v_exp_f32_e32 v84, v84
	v_exp_f32_e32 v85, v85
	v_add_f32_e32 v192, v84, v192
	v_add_f32_e32 v192, v85, v192
	s_waitcnt lgkmcnt(6)
	v_mfma_f32_32x32x16_bf16 v[96:111], v[204:207], v[144:147], v[96:111]
	v_exp_f32_e32 v86, v86
	v_exp_f32_e32 v87, v87
	v_cvt_pk_bf16_f32 v200, v80, v81
	v_cvt_pk_bf16_f32 v201, v82, v83
	v_cvt_pk_bf16_f32 v202, v84, v85
	v_cvt_pk_bf16_f32 v203, v86, v87
	v_add_f32_e32 v192, v86, v192
	v_add_f32_e32 v192, v87, v192
	s_waitcnt lgkmcnt(5)
	v_mfma_f32_32x32x16_bf16 v[112:127], v[208:211], v[140:143], v[112:127]
	v_exp_f32_e32 v88, v88
	v_exp_f32_e32 v89, v89
	v_add_f32_e32 v192, v88, v192
	v_add_f32_e32 v192, v89, v192
	s_waitcnt lgkmcnt(4)
	v_mfma_f32_32x32x16_bf16 v[96:111], v[212:215], v[140:143], v[96:111]
	v_exp_f32_e32 v90, v90
	v_exp_f32_e32 v91, v91
	v_add_f32_e32 v192, v90, v192
	v_add_f32_e32 v192, v91, v192
	ds_read_b64_tr_b16 v[204:205], v175 offset:49152
	ds_read_b64_tr_b16 v[206:207], v176 offset:49152
	ds_read_b64_tr_b16 v[208:209], v177 offset:49152
	ds_read_b64_tr_b16 v[210:211], v178 offset:49152
	ds_read_b64_tr_b16 v[212:213], v179 offset:49152
	ds_read_b64_tr_b16 v[214:215], v182 offset:49152
	ds_read_b64_tr_b16 v[232:233], v183 offset:49152
	ds_read_b64_tr_b16 v[234:235], v184 offset:49152
	s_waitcnt lgkmcnt(11)
	v_mfma_f32_32x32x16_bf16 v[112:127], v[216:219], v[136:139], v[112:127]
	v_exp_f32_e32 v92, v92
	v_exp_f32_e32 v93, v93
	v_add_f32_e32 v192, v92, v192
	v_add_f32_e32 v192, v93, v192
	s_waitcnt lgkmcnt(10)
	v_mfma_f32_32x32x16_bf16 v[96:111], v[220:223], v[136:139], v[96:111]
	v_exp_f32_e32 v94, v94
	v_exp_f32_e32 v95, v95
	v_cvt_pk_bf16_f32 v216, v88, v89
	v_cvt_pk_bf16_f32 v217, v90, v91
	v_cvt_pk_bf16_f32 v218, v92, v93
	v_cvt_pk_bf16_f32 v219, v94, v95
	s_waitcnt lgkmcnt(9)
	v_mfma_f32_32x32x16_bf16 v[112:127], v[224:227], v[132:135], v[112:127]
	v_add_f32_e32 v192, v94, v192
	v_add_f32_e32 v192, v95, v192
	s_waitcnt lgkmcnt(8)
	v_mfma_f32_32x32x16_bf16 v[96:111], v[228:231], v[132:135], v[96:111]
	ds_read_b64_tr_b16 v[220:221], v175 offset:53248
	ds_read_b64_tr_b16 v[222:223], v176 offset:53248
	ds_read_b64_tr_b16 v[224:225], v177 offset:53248
	ds_read_b64_tr_b16 v[226:227], v178 offset:53248
	ds_read_b64_tr_b16 v[228:229], v179 offset:53248
	ds_read_b64_tr_b16 v[230:231], v182 offset:53248
	ds_read_b64_tr_b16 v[236:237], v183 offset:53248
	ds_read_b64_tr_b16 v[238:239], v184 offset:53248
	s_waitcnt lgkmcnt(14)
	v_mfma_f32_32x32x16_bf16 v[48:63], v[204:207], v[200:203], v[48:63]
	v_exp_f32_e32 v64, v64
	v_exp_f32_e32 v65, v65
	v_add_f32_e32 v192, v64, v192
	v_add_f32_e32 v192, v65, v192
	s_waitcnt lgkmcnt(12)
	v_mfma_f32_32x32x16_bf16 v[32:47], v[208:211], v[200:203], v[32:47]
	v_exp_f32_e32 v66, v66
	v_exp_f32_e32 v67, v67
	v_add_f32_e32 v192, v66, v192
	v_add_f32_e32 v192, v67, v192
	s_waitcnt lgkmcnt(10)
	v_mfma_f32_32x32x16_bf16 v[16:31], v[212:215], v[200:203], v[16:31]
	v_exp_f32_e32 v68, v68
	v_exp_f32_e32 v69, v69
	v_add_f32_e32 v192, v68, v192
	v_add_f32_e32 v192, v69, v192
	s_waitcnt lgkmcnt(8)
	v_mfma_f32_32x32x16_bf16 v[0:15], v[232:235], v[200:203], v[0:15]
	v_exp_f32_e32 v70, v70
	v_exp_f32_e32 v71, v71
	v_cvt_pk_bf16_f32 v204, v64, v65
	v_cvt_pk_bf16_f32 v205, v66, v67
	v_cvt_pk_bf16_f32 v206, v68, v69
	v_cvt_pk_bf16_f32 v207, v70, v71
	ds_read_b64_tr_b16 v[200:201], v175 offset:57344
	ds_read_b64_tr_b16 v[202:203], v176 offset:57344
	ds_read_b64_tr_b16 v[208:209], v177 offset:57344
	ds_read_b64_tr_b16 v[210:211], v178 offset:57344
	ds_read_b64_tr_b16 v[212:213], v179 offset:57344
	ds_read_b64_tr_b16 v[214:215], v182 offset:57344
	ds_read_b64_tr_b16 v[232:233], v183 offset:57344
	ds_read_b64_tr_b16 v[234:235], v184 offset:57344
	s_waitcnt lgkmcnt(14)
	v_mfma_f32_32x32x16_bf16 v[48:63], v[220:223], v[216:219], v[48:63]
	v_exp_f32_e32 v72, v72
	v_add_f32_e32 v192, v70, v192
	v_add_f32_e32 v192, v71, v192
	s_waitcnt lgkmcnt(12)
	v_mfma_f32_32x32x16_bf16 v[32:47], v[224:227], v[216:219], v[32:47]
	v_exp_f32_e32 v73, v73
	v_add_f32_e32 v192, v72, v192
	s_waitcnt lgkmcnt(10)
	v_mfma_f32_32x32x16_bf16 v[16:31], v[228:231], v[216:219], v[16:31]
	v_exp_f32_e32 v74, v74
	v_add_f32_e32 v192, v73, v192
	s_waitcnt lgkmcnt(8)
	v_mfma_f32_32x32x16_bf16 v[0:15], v[236:239], v[216:219], v[0:15]
	v_exp_f32_e32 v75, v75
	v_add_f32_e32 v192, v74, v192
	ds_read_b64_tr_b16 v[216:217], v175 offset:61440
	ds_read_b64_tr_b16 v[218:219], v176 offset:61440
	ds_read_b64_tr_b16 v[220:221], v177 offset:61440
	ds_read_b64_tr_b16 v[222:223], v178 offset:61440
	ds_read_b64_tr_b16 v[224:225], v179 offset:61440
	ds_read_b64_tr_b16 v[226:227], v182 offset:61440
	ds_read_b64_tr_b16 v[228:229], v183 offset:61440
	ds_read_b64_tr_b16 v[230:231], v184 offset:61440
	s_waitcnt lgkmcnt(14)
	v_mfma_f32_32x32x16_bf16 v[48:63], v[200:203], v[204:207], v[48:63]
	v_exp_f32_e32 v76, v76
	v_add_f32_e32 v192, v75, v192
	s_waitcnt lgkmcnt(12)
	v_mfma_f32_32x32x16_bf16 v[32:47], v[208:211], v[204:207], v[32:47]
	v_exp_f32_e32 v77, v77
	v_add_f32_e32 v192, v76, v192
	s_waitcnt lgkmcnt(10)
	v_mfma_f32_32x32x16_bf16 v[16:31], v[212:215], v[204:207], v[16:31]
	v_exp_f32_e32 v78, v78
	v_add_f32_e32 v192, v77, v192
	s_waitcnt lgkmcnt(8)
	v_mfma_f32_32x32x16_bf16 v[0:15], v[232:235], v[204:207], v[0:15]
	v_exp_f32_e32 v79, v79
	v_cvt_pk_bf16_f32 v200, v72, v73
	v_cvt_pk_bf16_f32 v201, v74, v75
	v_cvt_pk_bf16_f32 v202, v76, v77
	v_cvt_pk_bf16_f32 v203, v78, v79
	s_waitcnt lgkmcnt(6)
	s_nop 0
	v_mfma_f32_32x32x16_bf16 v[48:63], v[216:219], v[200:203], v[48:63]
	v_add_f32_e32 v192, v78, v192
	v_add_f32_e32 v192, v79, v192
	s_waitcnt lgkmcnt(4)
	v_mfma_f32_32x32x16_bf16 v[32:47], v[220:223], v[200:203], v[32:47]
	v_add_f32_e32 v192, v188, v192
	s_waitcnt lgkmcnt(2)
	v_mfma_f32_32x32x16_bf16 v[16:31], v[224:227], v[200:203], v[16:31]
	s_waitcnt lgkmcnt(0)
	v_mfma_f32_32x32x16_bf16 v[0:15], v[228:231], v[200:203], v[0:15]
	s_waitcnt vmcnt(0) lgkmcnt(0)
	s_barrier
	s_cmp_ge_i32 s74, s20
	s_cbranch_scc1 .LBB0_303
	s_cmp_lg_u32 s37, 0
	s_cbranch_scc1 .LBB0_303
	s_cmp_lt_i32 s82, s68
	s_cselect_b32 s4, s82, s81
	v_lshl_add_u32 v128, s4, 13, v185
	s_mov_b32 m0, s73
	v_add_u32_e32 v241, 0x1000, v128
	global_load_lds_dwordx4 v128, s[22:23]
	s_mov_b32 m0, s75
	s_nop 0
	global_load_lds_dwordx4 v128, s[24:25]
	s_add_i32 m0, s73, 0x1000
	s_nop 0
	global_load_lds_dwordx4 v241, s[22:23]
	s_add_i32 m0, s75, 0x1000
	s_nop 0
	global_load_lds_dwordx4 v241, s[24:25]
.LBB0_303:
	s_lshl_b32 s100, s80, 14
	ds_read_b128 v[188:191], v171 offset:32768
	ds_read_b128 v[200:203], v171 offset:36864
	ds_read_b128 v[204:207], v174 offset:32768
	ds_read_b128 v[208:211], v174 offset:36864
	s_lshl_b32 s4, s80, 6
	s_cmp_lt_i32 s80, s68
	v_subrev_u32_e32 v64, s4, v159
	v_sub_u32_e32 v65, 0, v64
	s_cselect_b64 s[4:5], -1, 0
	v_cndmask_b32_e64 v64, v65, v64, s[4:5]
	v_cvt_f32_i32_e32 v64, v64
	v_cndmask_b32_e64 v67, v187, v186, s[4:5]
	v_cndmask_b32_e32 v128, 0, v67, vcc
	v_mul_f32_e64 v65, -v160, v64
	v_cvt_pk_bf16_f32 v65, v65, 0
	v_lshlrev_b32_e32 v65, 16, v65
	v_fma_f32 v64, -v160, v64, -v65
	v_cvt_pk_bf16_f32 v66, v64, 0
	v_lshlrev_b32_e32 v66, 16, v66
	v_sub_f32_e32 v64, v64, v66
	v_cvt_pk_bf16_f32 v65, v65, v66
	v_cvt_pk_bf16_f32 v64, v64, 0
	v_cndmask_b32_e32 v129, 0, v65, vcc
	v_cndmask_b32_e32 v130, 0, v64, vcc
	v_exp_f32_e32 v224, v112
	v_exp_f32_e32 v225, v113
	v_mfma_f32_32x32x16_bf16 v[80:95], v[152:155], v[128:131], 0
	v_add_f32_e32 v64, 0, v224
	v_add_f32_e32 v64, v225, v64
	s_cmp_lg_u32 s37, 0
	s_cbranch_scc1 .Lhv_skipB
	v_add_u32_e32 v240, s100, v170
	s_mov_b32 m0, s78
	v_add_u32_e32 v241, s100, v169
	global_load_lds_dwordx4 v240, s[6:7]
	s_mov_b32 m0, s79
	v_add_u32_e32 v240, 0x1000, v240
	global_load_lds_dwordx4 v241, s[6:7]
	s_add_i32 m0, s78, 0x1000
	v_add_u32_e32 v241, 0x1000, v241
	global_load_lds_dwordx4 v240, s[6:7]
	s_add_i32 m0, s79, 0x1000
	s_nop 0
	global_load_lds_dwordx4 v241, s[6:7]
.Lhv_skipB:
	v_exp_f32_e32 v226, v114
	v_exp_f32_e32 v227, v115
	v_add_f32_e32 v64, v226, v64
	v_add_f32_e32 v228, v227, v64
	v_mfma_f32_32x32x16_bf16 v[64:79], v[148:151], v[128:131], 0
	s_waitcnt lgkmcnt(3)
	v_mfma_f32_32x32x16_bf16 v[80:95], v[188:191], v[144:147], v[80:95]
	ds_read_b128 v[112:115], v172 offset:32768
	ds_read_b128 v[212:215], v172 offset:36864
	ds_read_b128 v[216:219], v173 offset:32768
	ds_read_b128 v[220:223], v173 offset:36864
	v_exp_f32_e32 v128, v116
	v_exp_f32_e32 v129, v117
	v_add_f32_e32 v116, v128, v228
	v_add_f32_e32 v130, v129, v116
	s_waitcnt lgkmcnt(6)
	v_mfma_f32_32x32x16_bf16 v[64:79], v[200:203], v[144:147], v[64:79]
	v_exp_f32_e32 v188, v118
	v_exp_f32_e32 v119, v119
	v_cvt_pk_bf16_f32 v116, v224, v225
	v_cvt_pk_bf16_f32 v117, v226, v227
	v_add_f32_e32 v118, v188, v130
	v_add_f32_e32 v130, v119, v118
	v_cvt_pk_bf16_f32 v118, v128, v129
	v_cvt_pk_bf16_f32 v119, v188, v119
	s_waitcnt lgkmcnt(5)
	v_mfma_f32_32x32x16_bf16 v[80:95], v[204:207], v[140:143], v[80:95]
	v_exp_f32_e32 v128, v120
	v_exp_f32_e32 v129, v121
	v_add_f32_e32 v120, v128, v130
	v_add_f32_e32 v120, v129, v120
	s_waitcnt lgkmcnt(4)
	v_mfma_f32_32x32x16_bf16 v[64:79], v[208:211], v[140:143], v[64:79]
	v_exp_f32_e32 v130, v122
	v_exp_f32_e32 v224, v123
	v_add_f32_e32 v120, v130, v120
	v_add_f32_e32 v225, v224, v120
	ds_read_b64_tr_b16 v[120:121], v175 offset:16384
	ds_read_b64_tr_b16 v[122:123], v176 offset:16384
	ds_read_b64_tr_b16 v[188:189], v177 offset:16384
	ds_read_b64_tr_b16 v[190:191], v178 offset:16384
	ds_read_b64_tr_b16 v[200:201], v179 offset:16384
	ds_read_b64_tr_b16 v[202:203], v182 offset:16384
	ds_read_b64_tr_b16 v[204:205], v183 offset:16384
	ds_read_b64_tr_b16 v[206:207], v184 offset:16384
	s_waitcnt lgkmcnt(11)
	v_mfma_f32_32x32x16_bf16 v[80:95], v[112:115], v[136:139], v[80:95]
	v_exp_f32_e32 v124, v124
	v_exp_f32_e32 v125, v125
	v_add_f32_e32 v112, v124, v225
	v_add_f32_e32 v114, v125, v112
	s_waitcnt lgkmcnt(10)
	v_mfma_f32_32x32x16_bf16 v[64:79], v[212:215], v[136:139], v[64:79]
	v_exp_f32_e32 v115, v126
	v_exp_f32_e32 v126, v127
	v_cvt_pk_bf16_f32 v112, v128, v129
	v_cvt_pk_bf16_f32 v113, v130, v224
	v_add_f32_e32 v114, v115, v114
	v_add_f32_e32 v128, v126, v114
	v_cvt_pk_bf16_f32 v114, v124, v125
	v_cvt_pk_bf16_f32 v115, v115, v126
	s_waitcnt lgkmcnt(9)
	v_mfma_f32_32x32x16_bf16 v[80:95], v[216:219], v[132:135], v[80:95]
	s_waitcnt lgkmcnt(8)
	v_mfma_f32_32x32x16_bf16 v[64:79], v[220:223], v[132:135], v[64:79]
	ds_read_b64_tr_b16 v[124:125], v175 offset:20480
	ds_read_b64_tr_b16 v[126:127], v176 offset:20480
	ds_read_b64_tr_b16 v[208:209], v177 offset:20480
	ds_read_b64_tr_b16 v[210:211], v178 offset:20480
	ds_read_b64_tr_b16 v[212:213], v179 offset:20480
	ds_read_b64_tr_b16 v[214:215], v182 offset:20480
	ds_read_b64_tr_b16 v[216:217], v183 offset:20480
	ds_read_b64_tr_b16 v[218:219], v184 offset:20480
	s_waitcnt lgkmcnt(14)
	v_mfma_f32_32x32x16_bf16 v[48:63], v[120:123], v[116:119], v[48:63]
	v_exp_f32_e32 v96, v96
	v_exp_f32_e32 v97, v97
	v_add_f32_e32 v120, v96, v128
	v_add_f32_e32 v120, v97, v120
	s_waitcnt lgkmcnt(12)
	v_mfma_f32_32x32x16_bf16 v[32:47], v[188:191], v[116:119], v[32:47]
	v_exp_f32_e32 v98, v98
	v_exp_f32_e32 v99, v99
	v_add_f32_e32 v120, v98, v120
	v_add_f32_e32 v120, v99, v120
	s_waitcnt lgkmcnt(10)
	v_mfma_f32_32x32x16_bf16 v[16:31], v[200:203], v[116:119], v[16:31]
	v_exp_f32_e32 v100, v100
	v_exp_f32_e32 v101, v101
	v_add_f32_e32 v120, v100, v120
	v_add_f32_e32 v120, v101, v120
	s_waitcnt lgkmcnt(8)
	v_mfma_f32_32x32x16_bf16 v[0:15], v[204:207], v[116:119], v[0:15]
	v_exp_f32_e32 v102, v102
	v_exp_f32_e32 v103, v103
	v_cvt_pk_bf16_f32 v96, v96, v97
	v_cvt_pk_bf16_f32 v97, v98, v99
	v_add_f32_e32 v98, v102, v120
	v_add_f32_e32 v128, v103, v98
	v_cvt_pk_bf16_f32 v98, v100, v101
	v_cvt_pk_bf16_f32 v99, v102, v103
	ds_read_b64_tr_b16 v[100:101], v175 offset:24576
	ds_read_b64_tr_b16 v[102:103], v176 offset:24576
	ds_read_b64_tr_b16 v[116:117], v177 offset:24576
	ds_read_b64_tr_b16 v[118:119], v178 offset:24576
	ds_read_b64_tr_b16 v[120:121], v179 offset:24576
	ds_read_b64_tr_b16 v[122:123], v182 offset:24576
	ds_read_b64_tr_b16 v[188:189], v183 offset:24576
	ds_read_b64_tr_b16 v[190:191], v184 offset:24576
	s_waitcnt lgkmcnt(14)
	v_mfma_f32_32x32x16_bf16 v[48:63], v[124:127], v[112:115], v[48:63]
	v_exp_f32_e32 v129, v104
	s_nop 0
	v_add_f32_e32 v104, v129, v128
	s_waitcnt lgkmcnt(12)
	v_mfma_f32_32x32x16_bf16 v[32:47], v[208:211], v[112:115], v[32:47]
	v_exp_f32_e32 v128, v105
	s_nop 0
	v_add_f32_e32 v104, v128, v104
	s_waitcnt lgkmcnt(10)
	v_mfma_f32_32x32x16_bf16 v[16:31], v[212:215], v[112:115], v[16:31]
	v_exp_f32_e32 v130, v106
	s_nop 0
	v_add_f32_e32 v104, v130, v104
	s_waitcnt lgkmcnt(8)
	v_mfma_f32_32x32x16_bf16 v[0:15], v[216:219], v[112:115], v[0:15]
	v_exp_f32_e32 v204, v107
	s_nop 0
	v_add_f32_e32 v205, v204, v104
	ds_read_b64_tr_b16 v[104:105], v175 offset:28672
	ds_read_b64_tr_b16 v[106:107], v176 offset:28672
	ds_read_b64_tr_b16 v[112:113], v177 offset:28672
	ds_read_b64_tr_b16 v[114:115], v178 offset:28672
	ds_read_b64_tr_b16 v[124:125], v179 offset:28672
	ds_read_b64_tr_b16 v[126:127], v182 offset:28672
	ds_read_b64_tr_b16 v[200:201], v183 offset:28672
	ds_read_b64_tr_b16 v[202:203], v184 offset:28672
	s_waitcnt lgkmcnt(14)
	v_mfma_f32_32x32x16_bf16 v[48:63], v[100:103], v[96:99], v[48:63]
	v_exp_f32_e32 v108, v108
	s_nop 0
	v_add_f32_e32 v100, v108, v205
	s_waitcnt lgkmcnt(12)
	v_mfma_f32_32x32x16_bf16 v[32:47], v[116:119], v[96:99], v[32:47]
	v_exp_f32_e32 v102, v109
	s_nop 0
	v_add_f32_e32 v100, v102, v100
	s_waitcnt lgkmcnt(10)
	v_mfma_f32_32x32x16_bf16 v[16:31], v[120:123], v[96:99], v[16:31]
	v_exp_f32_e32 v103, v110
	s_nop 0
	v_add_f32_e32 v109, v103, v100
	s_waitcnt lgkmcnt(8)
	v_mfma_f32_32x32x16_bf16 v[0:15], v[188:191], v[96:99], v[0:15]
	v_exp_f32_e32 v110, v111
	v_cvt_pk_bf16_f32 v100, v129, v128
	v_cvt_pk_bf16_f32 v101, v130, v204
	v_cvt_pk_bf16_f32 v102, v108, v102
	v_add_f32_e32 v108, v110, v109
	v_cvt_pk_bf16_f32 v103, v103, v110
	s_waitcnt lgkmcnt(6)
	s_nop 0
	v_mfma_f32_32x32x16_bf16 v[48:63], v[104:107], v[100:103], v[48:63]
	s_waitcnt lgkmcnt(4)
	v_mfma_f32_32x32x16_bf16 v[32:47], v[112:115], v[100:103], v[32:47]
	s_waitcnt lgkmcnt(2)
	v_mfma_f32_32x32x16_bf16 v[16:31], v[124:127], v[100:103], v[16:31]
	s_waitcnt lgkmcnt(0)
	v_mfma_f32_32x32x16_bf16 v[0:15], v[200:203], v[100:103], v[0:15]
	s_waitcnt vmcnt(0) lgkmcnt(0)
	s_barrier
	s_add_i32 s4, s74, 2
	s_add_i32 s5, s74, 1
	v_add_f32_e32 v188, v192, v108
	s_cmp_lt_i32 s5, s20
	s_cbranch_scc0 .LBB0_305
	s_mov_b32 s74, s4
	s_branch .LBB0_301
